# speedup vs baseline: 1.0121x; 1.0027x over previous
; #define CBAR() asm volatile("" ::: "memory")
; __device__ __forceinline__ void dsa_pv_stream(KParams& p, unsigned char* smem) {
;     int tid_o = threadIdx.x; asm volatile("" : "+v"(tid_o));
;     const int wid = __builtin_amdgcn_readfirstlane(tid_o >> 6), lane = tid_o & 63, fr = lane & 15, fq = lane >> 4;
;     const int G = gridDim.x;
;     int U = blockIdx.x;
;     if (U >= 8192) return;
;     unsigned char* vim = smem + wid * 8192;
;     unsigned short* ill = (unsigned short*)(smem + 65536) + wid * 512;
;     unsigned char* pim = smem + 73728 + wid * 2048;
;     const unsigned short* ilb = (const unsigned short*)(p.ws + WS_IDX);
;     const bf16_t* vcb = (const bf16_t*)(p.ws + WS_VC) + fr * 8;
;     const unsigned char* Pg = p.ws + WS_P;
;     unsigned wof[2][4];
; #pragma unroll
;     for (int j = 0; j < 4; ++j) { wof[0][j] = pv_off(fq * 4 + j, fr); wof[1][j] = pv_off(16 + fq * 4 + j, fr); }
;     unsigned tra[16];
;     {
;         const unsigned q = (unsigned)fr >> 2, pp = (unsigned)fr & 3u, vbase = (unsigned)(size_t)(__attribute__((address_space(3))) unsigned char*)vim;
; #pragma unroll
;         for (int n = 0; n < 8; ++n)
; #pragma unroll
;             for (int t = 0; t < 2; ++t) tra[n * 2 + t] = vbase + pv_off(8u * fq + 4u * t + q, 2u * n + (pp >> 1)) + 8u * (pp & 1u);
;     }
;     const int xoff = (fr & 3) * 512 + fq * 16;
;     u32x4 vx[4][4];
;     int cur = 0;
;     ...
;     {
;         const int bg = U & 7, t = (U >> 3) * 8 + wid; const size_t tok = (size_t)(bg >> 1) * SEQ + t;
;         *(u32x2*)(ill + lane * 4) = *(const u32x2*)(ilb + tok * 256 + lane * 4);
;         { const unsigned char* P0 = Pg + (tok * 2 + (bg & 1)) * 2048 + lane * 32; *(u32x4*)(pim + lane * 32) = *(const u32x4*)P0; *(u32x4*)(pim + lane * 32 + 16) = *(const u32x4*)(P0 + 16); }
;         CBAR();
;         const bf16_t* vb0 = vcb + (size_t)bg * SEQ * 128;
; #pragma unroll
;         for (int s = 0; s < 4; ++s) PV_ISSUE(s, ill, s, vb0);
;     }
.LBB0_1769:
	s_mov_b64 s[10:11], s[0:1]
	v_mov_b32_e32 v1, v166
	s_and_b64 vcc, exec, s[6:7]
	v_readfirstlane_b32 s8, v1
	s_cbranch_vccnz .LBB0_1768
	s_load_dwordx2 s[20:21], s[10:11], 0x80
	s_ashr_i32 s29, s8, 6
	s_lshl_b32 s8, s29, 11
	s_lshl_b32 s4, s29, 13
	s_add_i32 s12, s8, 0
	s_lshl_b32 s5, s29, 10
	s_add_i32 s12, s12, 0x12000
	s_add_i32 s13, s4, 0
	s_waitcnt lgkmcnt(0)
	s_add_u32 s8, s20, 0x3d730000
	s_addc_u32 s9, s21, 0
	s_add_i32 s30, s5, 0
	s_add_i32 s30, s30, 0x10000
	s_add_u32 s31, s20, 0x6730000
	s_addc_u32 s34, s21, 0
	s_add_i32 s4, s29, s24
	s_ashr_i32 s5, s4, 31
	s_add_u32 s4, s4, s25
	s_addc_u32 s5, s5, 0
	s_lshl_b64 s[22:23], s[4:5], 9
	s_add_u32 s22, s8, s22
	s_addc_u32 s23, s9, s23
	s_lshl_b64 s[4:5], s[4:5], 12
	s_add_u32 s4, s31, s4
	v_and_b32_e32 v16, 63, v1
	s_addc_u32 s5, s34, s5
	v_lshlrev_b32_e32 v0, 3, v16
	s_add_u32 s4, s4, s27
	s_addc_u32 s5, s5, 0
	v_lshlrev_b32_e32 v126, 5, v16
	global_load_dwordx2 v[10:11], v0, s[22:23]
	global_load_dwordx4 v[2:5], v126, s[4:5]
	global_load_dwordx4 v[6:9], v126, s[4:5] offset:16
	v_bfe_u32 v17, v1, 4, 2
	v_lshlrev_b32_e32 v12, 3, v1
	v_add_u32_e32 v13, s30, v0
	s_load_dwordx2 s[22:23], s[10:11], 0x58
	s_waitcnt vmcnt(16)
	v_lshlrev_b32_e32 v59, 3, v17
	s_waitcnt vmcnt(5)
	v_and_or_b32 v93, v12, 8, s13
	v_add_u32_e32 v12, s12, v126
	v_add_u32_e32 v139, s30, v59
	v_and_b32_e32 v18, 15, v1
	v_lshlrev_b32_e32 v124, 4, v18
	s_mov_b32 s15, s17
	v_bfe_u32 v19, v1, 2, 2
	v_bfe_u32 v37, v1, 1, 1
	v_or_b32_e32 v92, v59, v19
	v_cmp_eq_u32_e32 vcc, 2, v17
	v_and_b32_e32 v36, 3, v1
	v_bitop3_b32 v39, v17, v1, 15 bitop3:0x78
	v_bitop3_b32 v56, v17, v18, 4 bitop3:0x36
	v_bitop3_b32 v57, v17, v18, 8 bitop3:0x36
	v_bitop3_b32 v58, v17, v18, 12 bitop3:0x36
	v_lshlrev_b32_e32 v38, 10, v17
	v_lshlrev_b32_e32 v138, 2, v17
	v_lshlrev_b32_e32 v156, 2, v16
	v_mov_b32_e32 v127, v125
	v_lshl_or_b32 v157, v17, 7, v18
	v_lshlrev_b32_e32 v134, 1, v0
	v_add_u32_e32 v165, s12, v126
	s_mov_b32 s40, s2
	s_waitcnt vmcnt(2)
	ds_write_b64 v13, v[10:11]
	s_waitcnt vmcnt(1)
	ds_write_b128 v12, v[2:5]
	s_waitcnt vmcnt(0)
	ds_write_b128 v12, v[6:9] offset:16
	ds_read2_b64 v[2:5], v139 offset1:4
	v_lshl_add_u64 v[6:7], s[20:21], 0, v[124:125]
	v_lshl_add_u64 v[128:129], v[6:7], 0, s[18:19]
	v_lshl_add_u64 v[10:11], v[128:129], 0, s[14:15]
	ds_read2_b64 v[6:9], v139 offset0:8 offset1:12
	s_waitcnt lgkmcnt(0)
	v_lshlrev_b32_e32 v12, 8, v2
	v_and_b32_e32 v124, 0xffff00, v12
	v_lshlrev_b32_e32 v20, 8, v3
	v_lshl_add_u64 v[12:13], v[10:11], 0, v[124:125]
	v_lshlrev_b32_sdwa v124, v133, v2 dst_sel:DWORD dst_unused:UNUSED_PAD src0_sel:DWORD src1_sel:WORD_1
	v_lshl_add_u64 v[14:15], v[10:11], 0, v[124:125]
	v_and_b32_e32 v124, 0xffff00, v20
	v_lshlrev_b32_e32 v28, 8, v4
	global_load_dwordx4 v[20:23], v[12:13], off
	global_load_dwordx4 v[24:27], v[14:15], off
	v_lshl_add_u64 v[12:13], v[10:11], 0, v[124:125]
	v_lshlrev_b32_sdwa v124, v133, v3 dst_sel:DWORD dst_unused:UNUSED_PAD src0_sel:DWORD src1_sel:WORD_1
	v_lshl_add_u64 v[2:3], v[10:11], 0, v[124:125]
	v_and_b32_e32 v124, 0xffff00, v28
	v_lshlrev_b32_e32 v40, 8, v5
	global_load_dwordx4 v[28:31], v[12:13], off
	global_load_dwordx4 v[32:35], v[2:3], off
	v_lshl_add_u64 v[2:3], v[10:11], 0, v[124:125]
	v_lshlrev_b32_sdwa v124, v133, v4 dst_sel:DWORD dst_unused:UNUSED_PAD src0_sel:DWORD src1_sel:WORD_1
	v_lshl_add_u64 v[12:13], v[10:11], 0, v[124:125]
	v_and_b32_e32 v124, 0xffff00, v40
	v_lshlrev_b32_e32 v48, 8, v6
	global_load_dwordx4 v[40:43], v[2:3], off
	global_load_dwordx4 v[44:47], v[12:13], off
	v_lshl_add_u64 v[2:3], v[10:11], 0, v[124:125]
	v_lshlrev_b32_sdwa v124, v133, v5 dst_sel:DWORD dst_unused:UNUSED_PAD src0_sel:DWORD src1_sel:WORD_1
	v_lshl_add_u64 v[4:5], v[10:11], 0, v[124:125]
	v_and_b32_e32 v124, 0xffff00, v48
	v_lshlrev_b32_e32 v60, 8, v7
	global_load_dwordx4 v[52:55], v[2:3], off
	global_load_dwordx4 v[48:51], v[4:5], off
	v_lshl_add_u64 v[2:3], v[10:11], 0, v[124:125]
	v_lshlrev_b32_sdwa v124, v133, v6 dst_sel:DWORD dst_unused:UNUSED_PAD src0_sel:DWORD src1_sel:WORD_1
	v_lshl_add_u64 v[4:5], v[10:11], 0, v[124:125]
	v_and_b32_e32 v124, 0xffff00, v60
	v_lshlrev_b32_e32 v68, 8, v8
	global_load_dwordx4 v[64:67], v[2:3], off
	global_load_dwordx4 v[60:63], v[4:5], off
	v_lshl_add_u64 v[2:3], v[10:11], 0, v[124:125]
	v_lshlrev_b32_sdwa v124, v133, v7 dst_sel:DWORD dst_unused:UNUSED_PAD src0_sel:DWORD src1_sel:WORD_1
	v_lshl_add_u64 v[4:5], v[10:11], 0, v[124:125]
	v_and_b32_e32 v124, 0xffff00, v68
	v_lshlrev_b32_e32 v76, 8, v9
	global_load_dwordx4 v[72:75], v[2:3], off
	global_load_dwordx4 v[68:71], v[4:5], off
	v_lshl_add_u64 v[2:3], v[10:11], 0, v[124:125]
	v_lshlrev_b32_sdwa v124, v133, v8 dst_sel:DWORD dst_unused:UNUSED_PAD src0_sel:DWORD src1_sel:WORD_1
	v_lshl_add_u64 v[4:5], v[10:11], 0, v[124:125]
	v_and_b32_e32 v124, 0xffff00, v76
	global_load_dwordx4 v[80:83], v[2:3], off
	global_load_dwordx4 v[76:79], v[4:5], off
	v_lshl_add_u64 v[2:3], v[10:11], 0, v[124:125]
	v_lshlrev_b32_sdwa v124, v133, v9 dst_sel:DWORD dst_unused:UNUSED_PAD src0_sel:DWORD src1_sel:WORD_1
	v_lshl_add_u64 v[4:5], v[10:11], 0, v[124:125]
	global_load_dwordx4 v[88:91], v[2:3], off
	global_load_dwordx4 v[84:87], v[4:5], off
	v_lshrrev_b32_e32 v3, 3, v1
	v_and_b32_e32 v2, 12, v1
	v_and_b32_e32 v3, 2, v3
	v_or3_b32 v4, v3, v2, v37
	v_lshl_add_u32 v5, v92, 8, v93
	v_lshl_add_u32 v140, v4, 4, v5
	v_or_b32_e32 v4, 4, v59
	v_or_b32_e32 v6, v4, v19
	v_bfe_u32 v4, v4, 2, 2
	v_bitop3_b32 v7, v2, v37, v4 bitop3:0x36
	v_lshl_add_u32 v6, v6, 8, v93
	v_lshl_add_u32 v141, v7, 4, v6
	v_or_b32_e32 v7, 2, v37
	v_bitop3_b32 v8, v3, v7, v2 bitop3:0x36
	v_bitop3_b32 v7, v2, v7, v4 bitop3:0x36
; #define CBAR() asm volatile("" ::: "memory")
; __device__ __forceinline__ void dsa_pv_stream(KParams& p, unsigned char* smem) {
;     ...
;     for (;;) {
;         const bool last = (U + G >= 8192);
;         const int Un = last ? U : U + G;
;         const int bg = U & 7, t = (U >> 3) * 8 + wid; const size_t tok = (size_t)(bg >> 1) * SEQ + t;
;         const int bgn = Un & 7, tn = (Un >> 3) * 8 + wid; const size_t tokn = (size_t)(bgn >> 1) * SEQ + tn;
;         const u32x2 idxN = *(const u32x2*)(ilb + tokn * 256 + lane * 4);
;         const unsigned char* PN = Pg + (tokn * 2 + (bgn & 1)) * 2048 + lane * 32;
;         const u32x4 pN0 = *(const u32x4*)PN, pN1 = *(const u32x4*)(PN + 16);
;         const unsigned short* lc = ill + cur * 256; unsigned short* ln = ill + (cur ^ 1) * 256;
;         const bf16_t* vbc = vcb + (size_t)bg * SEQ * 128;
;         const bf16_t* vbn = vcb + (size_t)bgn * SEQ * 128;
;         f32x4 acc[8];
; #pragma unroll
;         for (int n = 0; n < 8; ++n) acc[n] = (f32x4){0, 0, 0, 0};
; #pragma unroll
;         for (int s = 0; s < 8; ++s) {
;             if (s == 4) { *(u32x2*)(ln + lane * 4) = idxN; CBAR(); }
; #pragma unroll
;             for (int j = 0; j < 4; ++j) { *(u32x4*)(vim + wof[0][j]) = vx[(2 * s) & 3][j]; *(u32x4*)(vim + wof[1][j]) = vx[(2 * s + 1) & 3][j]; }
;             CBAR();
;             if (2 * s + 4 < 16) { PV_ISSUE((2 * s) & 3, lc, 2 * s + 4, vbc); PV_ISSUE((2 * s + 1) & 3, lc, 2 * s + 5, vbc); }
;             else { PV_ISSUE((2 * s) & 3, ln, 2 * s + 4 - 16, vbn); PV_ISSUE((2 * s + 1) & 3, ln, 2 * s + 5 - 16, vbn); }
;             const u32x4 xf = *(const u32x4*)(pim + xoff + s * 64);
;             u32x2 y[16];
;             asm volatile("ds_read_b64_tr_b16 %0, %16\n\tds_read_b64_tr_b16 %1, %17\n\tds_read_b64_tr_b16 %2, %18\n\tds_read_b64_tr_b16 %3, %19\n\t"
;                          "ds_read_b64_tr_b16 %4, %20\n\tds_read_b64_tr_b16 %5, %21\n\tds_read_b64_tr_b16 %6, %22\n\tds_read_b64_tr_b16 %7, %23\n\t"
;                          "ds_read_b64_tr_b16 %8, %24\n\tds_read_b64_tr_b16 %9, %25\n\tds_read_b64_tr_b16 %10, %26\n\tds_read_b64_tr_b16 %11, %27\n\t"
;                          "ds_read_b64_tr_b16 %12, %28\n\tds_read_b64_tr_b16 %13, %29\n\tds_read_b64_tr_b16 %14, %30\n\tds_read_b64_tr_b16 %15, %31\n\t"
;                          "s_waitcnt lgkmcnt(0)"
	v_lshl_add_u32 v143, v7, 4, v6
	v_or_b32_e32 v7, 4, v37
	v_lshl_add_u32 v142, v8, 4, v5
	v_bitop3_b32 v8, v3, v7, v2 bitop3:0x36
	v_bitop3_b32 v7, v2, v7, v4 bitop3:0x36
	v_lshl_add_u32 v145, v7, 4, v6
	v_or_b32_e32 v7, 6, v37
	v_lshl_add_u32 v144, v8, 4, v5
	v_bitop3_b32 v8, v3, v7, v2 bitop3:0x36
	v_bitop3_b32 v7, v2, v7, v4 bitop3:0x36
	v_lshl_add_u32 v147, v7, 4, v6
	v_or_b32_e32 v7, 8, v37
	v_lshl_add_u32 v146, v8, 4, v5
	v_bitop3_b32 v8, v3, v7, v2 bitop3:0x36
	v_bitop3_b32 v7, v2, v7, v4 bitop3:0x36
	v_lshl_add_u32 v149, v7, 4, v6
	v_or_b32_e32 v7, 10, v37
	v_lshl_add_u32 v148, v8, 4, v5
	v_bitop3_b32 v8, v3, v7, v2 bitop3:0x36
	v_bitop3_b32 v7, v2, v7, v4 bitop3:0x36
	v_lshl_add_u32 v151, v7, 4, v6
	v_or_b32_e32 v7, 12, v37
	v_lshl_add_u32 v150, v8, 4, v5
	v_bitop3_b32 v8, v3, v7, v2 bitop3:0x36
	v_bitop3_b32 v7, v2, v7, v4 bitop3:0x36
	v_lshl_add_u32 v153, v7, 4, v6
	v_or_b32_e32 v7, 14, v37
	v_bitop3_b32 v3, v3, v7, v2 bitop3:0x36
	v_bitop3_b32 v2, v2, v7, v4 bitop3:0x36
	v_lshl_add_u32 v152, v8, 4, v5
	v_lshl_add_u32 v154, v3, 4, v5
	v_lshl_add_u32 v155, v2, 4, v6
	v_and_b32_e32 v2, 48, v1
	v_mov_b32_e32 v1, v125
	v_lshlrev_b32_e32 v3, 1, v18
	v_lshlrev_b32_e32 v4, 8, v17
	v_cndmask_b32_e64 v8, 3, 2, vcc
	v_cmp_ne_u32_e32 vcc, 1, v17
	v_lshl_add_u64 v[130:131], s[8:9], 0, v[0:1]
	v_lshl_add_u32 v1, v36, 9, s12
	v_add3_u32 v158, s12, v3, v4
	v_lshlrev_b32_e32 v3, 4, v16
	v_lshl_add_u32 v4, v39, 4, s13
	v_lshl_add_u32 v5, v56, 4, s13
	v_lshl_add_u32 v6, v57, 4, s13
	v_lshl_add_u32 v7, v58, 4, s13
	v_cndmask_b32_e32 v8, 1, v8, vcc
	v_cmp_lt_u32_e32 vcc, 15, v16
	s_mov_b32 s9, 0
	v_add_u32_e32 v159, v4, v38
	v_cndmask_b32_e32 v132, 0, v8, vcc
	v_add_u32_e32 v160, v5, v38
	v_add_u32_e32 v161, v6, v38
	v_add_u32_e32 v162, v7, v38
	v_add_u32_e32 v163, v1, v2
	v_add_u32_e32 v164, s12, v3
	s_mov_b32 s15, s75
	s_mov_b32 s98, -1
.LBB0_1771:
	s_add_i32 s35, s40, s44
	s_cmpk_gt_i32 s35, 0x1fff
	s_cselect_b32 s10, s40, s35
	s_lshl_b32 s4, s40, 12
	s_and_b32 s36, s40, -8
	s_and_b32 s37, s4, 0x6000
	s_and_b32 s4, s10, -8
	s_add_i32 s36, s36, s29
	s_lshl_b32 s5, s10, 12
	s_add_i32 s4, s4, s29
	s_and_b32 s12, s40, 7
	s_and_b32 s8, s10, 7
	s_ashr_i32 s38, s36, 31
	s_and_b32 s5, s5, 0x6000
	s_ashr_i32 s11, s4, 31
	s_add_u32 s4, s5, s4
	s_addc_u32 s5, 0, s11
	s_lshl_b32 s13, s10, 11
	s_lshl_b64 s[10:11], s[4:5], 9
	s_lshl_b64 s[4:5], s[4:5], 12
	s_and_b32 s13, s13, 0x800
	s_add_u32 s4, s31, s4
	s_addc_u32 s5, s34, s5
	s_add_u32 s4, s4, s13
	s_addc_u32 s5, s5, 0
	s_waitcnt vmcnt(15)
	ds_write_b128 v159, v[20:23]
	s_waitcnt vmcnt(11)
	ds_write_b128 v159, v[40:43] offset:4096
	ds_write_b128 v160, v[24:27] offset:256
	s_waitcnt vmcnt(10)
	ds_write_b128 v160, v[44:47] offset:4352
	ds_write_b128 v161, v[28:31] offset:512
	s_waitcnt vmcnt(9)
	ds_write_b128 v161, v[52:55] offset:4608
	ds_write_b128 v162, v[32:35] offset:768
	s_waitcnt vmcnt(8)
	ds_write_b128 v162, v[48:51] offset:4864
	v_lshl_add_u64 v[0:1], v[130:131], 0, s[10:11]
	v_lshl_add_u64 v[4:5], s[4:5], 0, v[126:127]
	v_lshl_add_u32 v24, s9, 9, v139
	global_load_dwordx2 v[22:23], v[0:1], off
	s_nop 0
	global_load_dwordx4 v[0:3], v[4:5], off offset:16
	s_nop 0
	global_load_dwordx4 v[4:7], v[4:5], off
	ds_read2_b64 v[8:11], v24 offset0:16 offset1:20
	ds_read_b128 v[12:15], v163
	s_lshl_b32 s16, s12, 21
	v_lshl_add_u64 v[20:21], v[128:129], 0, s[16:17]
	s_xor_b32 s16, s9, 1
	s_waitcnt lgkmcnt(1)
	v_lshlrev_b32_e32 v16, 8, v8
	v_and_b32_e32 v124, 0xffff00, v16
	v_lshlrev_b32_e32 v18, 8, v9
	v_lshl_add_u64 v[16:17], v[20:21], 0, v[124:125]
	v_lshlrev_b32_sdwa v124, v133, v8 dst_sel:DWORD dst_unused:UNUSED_PAD src0_sel:DWORD src1_sel:WORD_1
	v_lshl_add_u64 v[26:27], v[20:21], 0, v[124:125]
	v_and_b32_e32 v124, 0xffff00, v18
	v_lshlrev_b32_e32 v25, 8, v10
	v_lshl_add_u64 v[30:31], v[20:21], 0, v[124:125]
	v_lshlrev_b32_sdwa v124, v133, v9 dst_sel:DWORD dst_unused:UNUSED_PAD src0_sel:DWORD src1_sel:WORD_1
	v_lshl_add_u64 v[8:9], v[20:21], 0, v[124:125]
	v_and_b32_e32 v124, 0xffff00, v25
	v_lshlrev_b32_e32 v38, 8, v11
	global_load_dwordx4 v[16:19], v[16:17], off
	s_nop 0
	global_load_dwordx4 v[26:29], v[26:27], off
	s_nop 0
	global_load_dwordx4 v[30:33], v[30:31], off
	s_nop 0
	global_load_dwordx4 v[34:37], v[8:9], off
	v_lshl_add_u64 v[8:9], v[20:21], 0, v[124:125]
	v_lshlrev_b32_sdwa v124, v133, v10 dst_sel:DWORD dst_unused:UNUSED_PAD src0_sel:DWORD src1_sel:WORD_1
	v_lshl_add_u64 v[42:43], v[20:21], 0, v[124:125]
	v_and_b32_e32 v124, 0xffff00, v38
	global_load_dwordx4 v[38:41], v[8:9], off
	s_nop 0
	global_load_dwordx4 v[42:45], v[42:43], off
	v_lshl_add_u64 v[8:9], v[20:21], 0, v[124:125]
	v_lshlrev_b32_sdwa v124, v133, v11 dst_sel:DWORD dst_unused:UNUSED_PAD src0_sel:DWORD src1_sel:WORD_1
	v_lshl_add_u64 v[46:47], v[20:21], 0, v[124:125]
	global_load_dwordx4 v[8:11], v[8:9], off
	s_nop 0
	global_load_dwordx4 v[46:49], v[46:47], off
	ds_read_b64_tr_b16 v[112:113], v140
	ds_read_b64_tr_b16 v[114:115], v141
	ds_read_b64_tr_b16 v[108:109], v142
	ds_read_b64_tr_b16 v[110:111], v143
	ds_read_b64_tr_b16 v[104:105], v144
	ds_read_b64_tr_b16 v[106:107], v145
	ds_read_b64_tr_b16 v[100:101], v146
	ds_read_b64_tr_b16 v[102:103], v147
	ds_read_b64_tr_b16 v[96:97], v148
	ds_read_b64_tr_b16 v[98:99], v149
	ds_read_b64_tr_b16 v[92:93], v150
	ds_read_b64_tr_b16 v[94:95], v151
	ds_read_b64_tr_b16 v[54:55], v152
	ds_read_b64_tr_b16 v[56:57], v153
	ds_read_b64_tr_b16 v[50:51], v154
	ds_read_b64_tr_b16 v[52:53], v155
	s_waitcnt lgkmcnt(0)
	s_waitcnt vmcnt(18)
	ds_write_b128 v159, v[64:67]
	s_waitcnt vmcnt(14)
	ds_write_b128 v159, v[80:83] offset:4096
	ds_write_b128 v160, v[60:63] offset:256
	s_waitcnt vmcnt(13)
	ds_write_b128 v160, v[76:79] offset:4352
	ds_write_b128 v161, v[72:75] offset:512
	s_waitcnt vmcnt(12)
	ds_write_b128 v161, v[88:91] offset:4608
	ds_write_b128 v162, v[68:71] offset:768
	s_waitcnt vmcnt(11)
	ds_write_b128 v162, v[84:87] offset:4864
	ds_read2_b64 v[66:69], v24 offset0:24 offset1:28
	ds_read_b128 v[70:73], v163 offset:64
	s_waitcnt lgkmcnt(10)
	v_mfma_f32_16x16x32_bf16 v[112:115], v[12:15], v[112:115], 0
	s_lshl_b32 s4, s16, 9
	s_add_i32 s9, s30, s4
	s_waitcnt lgkmcnt(1)
	v_lshlrev_b32_e32 v25, 8, v66
	v_and_b32_e32 v124, 0xffff00, v25
	v_mfma_f32_16x16x32_bf16 v[108:111], v[12:15], v[108:111], 0
	v_lshlrev_b32_e32 v80, 8, v68
	v_lshlrev_b32_e32 v86, 8, v69
	v_lshl_add_u32 v135, v138, 1, s9
	v_mfma_f32_16x16x32_bf16 v[104:107], v[12:15], v[104:107], 0
	s_mov_b32 s5, s17
	s_lshl_b32 s4, s8, 21
	v_lshl_add_u64 v[136:137], v[128:129], 0, s[4:5]
	v_mfma_f32_16x16x32_bf16 v[100:103], v[12:15], v[100:103], 0
	s_and_b32 s39, s15, 0x200
	s_cmp_eq_u32 s39, s98
	s_cbranch_scc1 .Lpv_beta_ok
; #define CBAR() asm volatile("" ::: "memory")
; __device__ __forceinline__ void dsa_pv_stream(KParams& p, unsigned char* smem) {
;     ...
;         for (int s = 0; s < 8; ++s) {
;             if (s == 4) { *(u32x2*)(ln + lane * 4) = idxN; CBAR(); }
; #pragma unroll
;             for (int j = 0; j < 4; ++j) { *(u32x4*)(vim + wof[0][j]) = vx[(2 * s) & 3][j]; *(u32x4*)(vim + wof[1][j]) = vx[(2 * s + 1) & 3][j]; }
;             CBAR();
;             if (2 * s + 4 < 16) { PV_ISSUE((2 * s) & 3, lc, 2 * s + 4, vbc); PV_ISSUE((2 * s + 1) & 3, lc, 2 * s + 5, vbc); }
;             else { PV_ISSUE((2 * s) & 3, ln, 2 * s + 4 - 16, vbn); PV_ISSUE((2 * s + 1) & 3, ln, 2 * s + 5 - 16, vbn); }
;             const u32x4 xf = *(const u32x4*)(pim + xoff + s * 64);
;             u32x2 y[16];
;             asm volatile("ds_read_b64_tr_b16 %0, %16\n\tds_read_b64_tr_b16 %1, %17\n\tds_read_b64_tr_b16 %2, %18\n\tds_read_b64_tr_b16 %3, %19\n\t"
;                          "ds_read_b64_tr_b16 %4, %20\n\tds_read_b64_tr_b16 %5, %21\n\tds_read_b64_tr_b16 %6, %22\n\tds_read_b64_tr_b16 %7, %23\n\t"
;                          "ds_read_b64_tr_b16 %8, %24\n\tds_read_b64_tr_b16 %9, %25\n\tds_read_b64_tr_b16 %10, %26\n\tds_read_b64_tr_b16 %11, %27\n\t"
;                          "ds_read_b64_tr_b16 %12, %28\n\tds_read_b64_tr_b16 %13, %29\n\tds_read_b64_tr_b16 %14, %30\n\tds_read_b64_tr_b16 %15, %31\n\t"
;                          "s_waitcnt lgkmcnt(0)"
;                          : "=&v"(y[0]), "=&v"(y[1]), "=&v"(y[2]), "=&v"(y[3]), "=&v"(y[4]), "=&v"(y[5]), "=&v"(y[6]), "=&v"(y[7]),
;                            "=&v"(y[8]), "=&v"(y[9]), "=&v"(y[10]), "=&v"(y[11]), "=&v"(y[12]), "=&v"(y[13]), "=&v"(y[14]), "=&v"(y[15])
;                          : "v"(tra[0]), "v"(tra[1]), "v"(tra[2]), "v"(tra[3]), "v"(tra[4]), "v"(tra[5]), "v"(tra[6]), "v"(tra[7]),
;                            "v"(tra[8]), "v"(tra[9]), "v"(tra[10]), "v"(tra[11]), "v"(tra[12]), "v"(tra[13]), "v"(tra[14]), "v"(tra[15])
;                          : "memory");
; #pragma unroll
;             for (int n = 0; n < 8; ++n) { const u32x4 yf = {y[2 * n].x, y[2 * n].y, y[2 * n + 1].x, y[2 * n + 1].y}; acc[n] = mfma16(xf, yf, acc[n]); }
;         }
;         CBAR();
;         {
;             const int hc = ((bg & 1) * 4 + fq) * 128;
; #pragma unroll
;             for (int n = 0; n < 8; ++n) {
	s_mov_b32 s98, s39
	v_or_b32_e32 v232, s39, v157
	v_lshlrev_b32_e32 v232, 2, v232
	global_load_dword v224, v232, s[22:23]
	global_load_dword v225, v232, s[22:23] offset:64
	global_load_dword v226, v232, s[22:23] offset:128
	global_load_dword v227, v232, s[22:23] offset:192
	global_load_dword v228, v232, s[22:23] offset:256
	global_load_dword v229, v232, s[22:23] offset:320
	global_load_dword v230, v232, s[22:23] offset:384
	global_load_dword v231, v232, s[22:23] offset:448
	s_waitcnt vmcnt(0)
.Lpv_beta_ok:
	v_cmp_eq_u32_e64 s[10:11], 2, v132
	v_cmp_eq_u32_e64 s[12:13], 3, v132
	v_mfma_f32_16x16x32_bf16 v[58:61], v[12:15], v[96:99], 0
	s_add_u32 s4, s37, s36
	s_addc_u32 s5, 0, s38
	s_lshl_b64 s[4:5], s[4:5], 12
	v_mfma_f32_16x16x32_bf16 v[62:65], v[12:15], v[92:95], 0
	s_add_u32 s4, s20, s4
	s_addc_u32 s5, s21, s5
	s_lshl_b32 s36, s39, 1
	v_mfma_f32_16x16x32_bf16 v[54:57], v[12:15], v[54:57], 0
	s_add_u32 s4, s4, s36
	s_addc_u32 s5, s5, 0
	s_add_i32 s15, s15, s76
	v_mfma_f32_16x16x32_bf16 v[12:15], v[12:15], v[50:53], 0
	v_lshlrev_b32_e32 v52, 8, v67
	v_lshl_add_u64 v[50:51], v[20:21], 0, v[124:125]
	v_lshlrev_b32_sdwa v124, v133, v66 dst_sel:DWORD dst_unused:UNUSED_PAD src0_sel:DWORD src1_sel:WORD_1
	v_lshl_add_u64 v[74:75], v[20:21], 0, v[124:125]
	v_and_b32_e32 v124, 0xffff00, v52
	v_lshl_add_u64 v[78:79], v[20:21], 0, v[124:125]
	v_lshlrev_b32_sdwa v124, v133, v67 dst_sel:DWORD dst_unused:UNUSED_PAD src0_sel:DWORD src1_sel:WORD_1
	v_lshl_add_u64 v[66:67], v[20:21], 0, v[124:125]
	v_and_b32_e32 v124, 0xffff00, v80
	global_load_dwordx4 v[50:53], v[50:51], off
	s_nop 0
	global_load_dwordx4 v[74:77], v[74:75], off
	s_nop 0
	global_load_dwordx4 v[78:81], v[78:79], off
	s_nop 0
	global_load_dwordx4 v[82:85], v[66:67], off
	v_lshl_add_u64 v[66:67], v[20:21], 0, v[124:125]
	v_lshlrev_b32_sdwa v124, v133, v68 dst_sel:DWORD dst_unused:UNUSED_PAD src0_sel:DWORD src1_sel:WORD_1
	v_lshl_add_u64 v[90:91], v[20:21], 0, v[124:125]
	v_and_b32_e32 v124, 0xffff00, v86
	global_load_dwordx4 v[86:89], v[66:67], off
	s_nop 0
	global_load_dwordx4 v[90:93], v[90:91], off
	v_lshl_add_u64 v[66:67], v[20:21], 0, v[124:125]
	v_lshlrev_b32_sdwa v124, v133, v69 dst_sel:DWORD dst_unused:UNUSED_PAD src0_sel:DWORD src1_sel:WORD_1
	v_lshl_add_u64 v[94:95], v[20:21], 0, v[124:125]
	global_load_dwordx4 v[66:69], v[66:67], off
	s_nop 0
	global_load_dwordx4 v[94:97], v[94:95], off
	ds_read_b64_tr_b16 v[196:197], v140
	ds_read_b64_tr_b16 v[198:199], v141
	ds_read_b64_tr_b16 v[192:193], v142
	ds_read_b64_tr_b16 v[194:195], v143
	ds_read_b64_tr_b16 v[188:189], v144
	ds_read_b64_tr_b16 v[190:191], v145
	ds_read_b64_tr_b16 v[184:185], v146
	ds_read_b64_tr_b16 v[186:187], v147
	ds_read_b64_tr_b16 v[180:181], v148
	ds_read_b64_tr_b16 v[182:183], v149
	ds_read_b64_tr_b16 v[176:177], v150
	ds_read_b64_tr_b16 v[178:179], v151
	ds_read_b64_tr_b16 v[120:121], v152
	ds_read_b64_tr_b16 v[122:123], v153
	ds_read_b64_tr_b16 v[116:117], v154
	ds_read_b64_tr_b16 v[118:119], v155
	s_waitcnt lgkmcnt(0)
	s_waitcnt vmcnt(15)
	ds_write_b128 v159, v[16:19]
	s_waitcnt vmcnt(14)
	ds_write_b128 v160, v[26:29] offset:256
	s_waitcnt vmcnt(13)
	ds_write_b128 v161, v[30:33] offset:512
	s_waitcnt vmcnt(12)
	ds_write_b128 v162, v[34:37] offset:768
	s_waitcnt vmcnt(11)
	ds_write_b128 v159, v[38:41] offset:4096
	s_waitcnt vmcnt(10)
	ds_write_b128 v160, v[42:45] offset:4352
	s_waitcnt vmcnt(9)
	ds_write_b128 v161, v[8:11] offset:4608
	s_waitcnt vmcnt(8)
	ds_write_b128 v162, v[46:49] offset:4864
	ds_read2_b64 v[8:11], v24 offset0:32 offset1:36
	ds_read_b128 v[16:19], v163 offset:128
	s_waitcnt lgkmcnt(10)
	v_mfma_f32_16x16x32_bf16 v[58:61], v[70:73], v[180:183], v[58:61]
	s_mov_b32 s40, s35
	s_cmpk_lt_i32 s35, 0x2000
	s_waitcnt lgkmcnt(1)
	v_lshlrev_b32_e32 v25, 8, v8
	v_and_b32_e32 v124, 0xffff00, v25
	v_lshlrev_b32_e32 v28, 8, v9
	v_lshl_add_u64 v[26:27], v[20:21], 0, v[124:125]
	v_lshlrev_b32_sdwa v124, v133, v8 dst_sel:DWORD dst_unused:UNUSED_PAD src0_sel:DWORD src1_sel:WORD_1
	v_lshl_add_u64 v[30:31], v[20:21], 0, v[124:125]
	v_and_b32_e32 v124, 0xffff00, v28
	v_lshlrev_b32_e32 v36, 8, v10
	v_lshl_add_u64 v[34:35], v[20:21], 0, v[124:125]
	v_lshlrev_b32_sdwa v124, v133, v9 dst_sel:DWORD dst_unused:UNUSED_PAD src0_sel:DWORD src1_sel:WORD_1
	v_lshl_add_u64 v[8:9], v[20:21], 0, v[124:125]
	v_and_b32_e32 v124, 0xffff00, v36
	v_lshlrev_b32_e32 v42, 8, v11
	global_load_dwordx4 v[26:29], v[26:27], off
	s_nop 0
	global_load_dwordx4 v[30:33], v[30:31], off
	s_nop 0
	global_load_dwordx4 v[34:37], v[34:35], off
	s_nop 0
	global_load_dwordx4 v[38:41], v[8:9], off
	v_lshl_add_u64 v[8:9], v[20:21], 0, v[124:125]
	v_lshlrev_b32_sdwa v124, v133, v10 dst_sel:DWORD dst_unused:UNUSED_PAD src0_sel:DWORD src1_sel:WORD_1
	v_lshl_add_u64 v[46:47], v[20:21], 0, v[124:125]
	v_and_b32_e32 v124, 0xffff00, v42
	v_mfma_f32_16x16x32_bf16 v[62:65], v[70:73], v[176:179], v[62:65]
	global_load_dwordx4 v[42:45], v[8:9], off
	s_nop 0
	global_load_dwordx4 v[46:49], v[46:47], off
	v_lshl_add_u64 v[8:9], v[20:21], 0, v[124:125]
	v_lshlrev_b32_sdwa v124, v133, v11 dst_sel:DWORD dst_unused:UNUSED_PAD src0_sel:DWORD src1_sel:WORD_1
	v_mfma_f32_16x16x32_bf16 v[54:57], v[70:73], v[120:123], v[54:57]
	v_lshl_add_u64 v[10:11], v[20:21], 0, v[124:125]
	v_mfma_f32_16x16x32_bf16 v[112:115], v[70:73], v[196:199], v[112:115]
	v_mfma_f32_16x16x32_bf16 v[108:111], v[70:73], v[192:195], v[108:111]
	v_mfma_f32_16x16x32_bf16 v[104:107], v[70:73], v[188:191], v[104:107]
	v_mfma_f32_16x16x32_bf16 v[98:101], v[70:73], v[184:187], v[100:103]
	v_mfma_f32_16x16x32_bf16 v[12:15], v[70:73], v[116:119], v[12:15]
	global_load_dwordx4 v[70:73], v[8:9], off
	global_load_dwordx4 v[116:119], v[10:11], off
	ds_read_b64_tr_b16 v[196:197], v140
	ds_read_b64_tr_b16 v[198:199], v141
	ds_read_b64_tr_b16 v[192:193], v142
	ds_read_b64_tr_b16 v[194:195], v143
	ds_read_b64_tr_b16 v[188:189], v144
	ds_read_b64_tr_b16 v[190:191], v145
	ds_read_b64_tr_b16 v[184:185], v146
	ds_read_b64_tr_b16 v[186:187], v147
	ds_read_b64_tr_b16 v[180:181], v148
	ds_read_b64_tr_b16 v[182:183], v149
	ds_read_b64_tr_b16 v[176:177], v150
	ds_read_b64_tr_b16 v[178:179], v151
	ds_read_b64_tr_b16 v[8:9], v152
	ds_read_b64_tr_b16 v[10:11], v153
	ds_read_b64_tr_b16 v[120:121], v154
	ds_read_b64_tr_b16 v[122:123], v155
	s_waitcnt lgkmcnt(0)
; #define CBAR() asm volatile("" ::: "memory")
; __device__ __forceinline__ void dsa_pv_stream(KParams& p, unsigned char* smem) {
;     ...
;         for (int s = 0; s < 8; ++s) {
;             if (s == 4) { *(u32x2*)(ln + lane * 4) = idxN; CBAR(); }
; #pragma unroll
;             for (int j = 0; j < 4; ++j) { *(u32x4*)(vim + wof[0][j]) = vx[(2 * s) & 3][j]; *(u32x4*)(vim + wof[1][j]) = vx[(2 * s + 1) & 3][j]; }
;             CBAR();
;             if (2 * s + 4 < 16) { PV_ISSUE((2 * s) & 3, lc, 2 * s + 4, vbc); PV_ISSUE((2 * s + 1) & 3, lc, 2 * s + 5, vbc); }
;             else { PV_ISSUE((2 * s) & 3, ln, 2 * s + 4 - 16, vbn); PV_ISSUE((2 * s + 1) & 3, ln, 2 * s + 5 - 16, vbn); }
;             const u32x4 xf = *(const u32x4*)(pim + xoff + s * 64);
;             u32x2 y[16];
;             asm volatile("ds_read_b64_tr_b16 %0, %16\n\tds_read_b64_tr_b16 %1, %17\n\tds_read_b64_tr_b16 %2, %18\n\tds_read_b64_tr_b16 %3, %19\n\t"
;                          "ds_read_b64_tr_b16 %4, %20\n\tds_read_b64_tr_b16 %5, %21\n\tds_read_b64_tr_b16 %6, %22\n\tds_read_b64_tr_b16 %7, %23\n\t"
;                          "ds_read_b64_tr_b16 %8, %24\n\tds_read_b64_tr_b16 %9, %25\n\tds_read_b64_tr_b16 %10, %26\n\tds_read_b64_tr_b16 %11, %27\n\t"
;                          "ds_read_b64_tr_b16 %12, %28\n\tds_read_b64_tr_b16 %13, %29\n\tds_read_b64_tr_b16 %14, %30\n\tds_read_b64_tr_b16 %15, %31\n\t"
;                          "s_waitcnt lgkmcnt(0)"
;                          : "=&v"(y[0]), "=&v"(y[1]), "=&v"(y[2]), "=&v"(y[3]), "=&v"(y[4]), "=&v"(y[5]), "=&v"(y[6]), "=&v"(y[7]),
;                            "=&v"(y[8]), "=&v"(y[9]), "=&v"(y[10]), "=&v"(y[11]), "=&v"(y[12]), "=&v"(y[13]), "=&v"(y[14]), "=&v"(y[15])
;                          : "v"(tra[0]), "v"(tra[1]), "v"(tra[2]), "v"(tra[3]), "v"(tra[4]), "v"(tra[5]), "v"(tra[6]), "v"(tra[7]),
;                            "v"(tra[8]), "v"(tra[9]), "v"(tra[10]), "v"(tra[11]), "v"(tra[12]), "v"(tra[13]), "v"(tra[14]), "v"(tra[15])
;                          : "memory");
; #pragma unroll
;             for (int n = 0; n < 8; ++n) { const u32x4 yf = {y[2 * n].x, y[2 * n].y, y[2 * n + 1].x, y[2 * n + 1].y}; acc[n] = mfma16(xf, yf, acc[n]); }
	s_waitcnt vmcnt(15)
	ds_write_b128 v159, v[50:53]
	s_waitcnt vmcnt(11)
	ds_write_b128 v159, v[86:89] offset:4096
	ds_write_b128 v160, v[74:77] offset:256
	s_waitcnt vmcnt(10)
	ds_write_b128 v160, v[90:93] offset:4352
	ds_write_b128 v161, v[78:81] offset:512
	s_waitcnt vmcnt(9)
	ds_write_b128 v161, v[66:69] offset:4608
	ds_write_b128 v162, v[82:85] offset:768
	s_waitcnt vmcnt(8)
	ds_write_b128 v162, v[94:97] offset:4864
	s_waitcnt lgkmcnt(8)
	v_mfma_f32_16x16x32_bf16 v[50:53], v[16:19], v[180:183], v[58:61]
	v_mfma_f32_16x16x32_bf16 v[58:61], v[16:19], v[176:179], v[62:65]
	v_mfma_f32_16x16x32_bf16 v[54:57], v[16:19], v[8:11], v[54:57]
	s_nop 1
	ds_read2_b64 v[62:65], v24 offset0:40 offset1:44
	ds_read_b128 v[8:11], v163 offset:192
	s_waitcnt lgkmcnt(1)
	v_lshlrev_b32_e32 v25, 8, v63
	v_mfma_f32_16x16x32_bf16 v[112:115], v[16:19], v[196:199], v[112:115]
	v_lshlrev_b32_e32 v78, 8, v64
	v_lshlrev_b32_e32 v86, 8, v65
	v_mfma_f32_16x16x32_bf16 v[108:111], v[16:19], v[192:195], v[108:111]
	v_mfma_f32_16x16x32_bf16 v[102:105], v[16:19], v[188:191], v[104:107]
	v_mfma_f32_16x16x32_bf16 v[98:101], v[16:19], v[184:187], v[98:101]
	v_mfma_f32_16x16x32_bf16 v[12:15], v[16:19], v[120:123], v[12:15]
	v_lshlrev_b32_e32 v16, 8, v62
	v_and_b32_e32 v124, 0xffff00, v16
	v_lshl_add_u64 v[16:17], v[20:21], 0, v[124:125]
	v_lshlrev_b32_sdwa v124, v133, v62 dst_sel:DWORD dst_unused:UNUSED_PAD src0_sel:DWORD src1_sel:WORD_1
	v_lshl_add_u64 v[18:19], v[20:21], 0, v[124:125]
	v_and_b32_e32 v124, 0xffff00, v25
	global_load_dwordx4 v[66:69], v[16:17], off
	global_load_dwordx4 v[74:77], v[18:19], off
	v_lshl_add_u64 v[16:17], v[20:21], 0, v[124:125]
	v_lshlrev_b32_sdwa v124, v133, v63 dst_sel:DWORD dst_unused:UNUSED_PAD src0_sel:DWORD src1_sel:WORD_1
	v_lshl_add_u64 v[18:19], v[20:21], 0, v[124:125]
	v_and_b32_e32 v124, 0xffff00, v78
	global_load_dwordx4 v[78:81], v[16:17], off
	global_load_dwordx4 v[82:85], v[18:19], off
	v_lshl_add_u64 v[16:17], v[20:21], 0, v[124:125]
	v_lshlrev_b32_sdwa v124, v133, v64 dst_sel:DWORD dst_unused:UNUSED_PAD src0_sel:DWORD src1_sel:WORD_1
	v_lshl_add_u64 v[18:19], v[20:21], 0, v[124:125]
	v_and_b32_e32 v124, 0xffff00, v86
	global_load_dwordx4 v[86:89], v[16:17], off
	global_load_dwordx4 v[90:93], v[18:19], off
	v_lshl_add_u64 v[16:17], v[20:21], 0, v[124:125]
	v_lshlrev_b32_sdwa v124, v133, v65 dst_sel:DWORD dst_unused:UNUSED_PAD src0_sel:DWORD src1_sel:WORD_1
	v_lshl_add_u64 v[18:19], v[20:21], 0, v[124:125]
	global_load_dwordx4 v[62:65], v[16:17], off
	global_load_dwordx4 v[94:97], v[18:19], off
	v_lshl_add_u32 v25, v156, 1, s9
	ds_read_b64_tr_b16 v[196:197], v140
	ds_read_b64_tr_b16 v[198:199], v141
	ds_read_b64_tr_b16 v[192:193], v142
	ds_read_b64_tr_b16 v[194:195], v143
	ds_read_b64_tr_b16 v[188:189], v144
	ds_read_b64_tr_b16 v[190:191], v145
	ds_read_b64_tr_b16 v[184:185], v146
	ds_read_b64_tr_b16 v[186:187], v147
	ds_read_b64_tr_b16 v[180:181], v148
	ds_read_b64_tr_b16 v[182:183], v149
	ds_read_b64_tr_b16 v[176:177], v150
	ds_read_b64_tr_b16 v[178:179], v151
	ds_read_b64_tr_b16 v[120:121], v152
	ds_read_b64_tr_b16 v[122:123], v153
	ds_read_b64_tr_b16 v[16:17], v154
	ds_read_b64_tr_b16 v[18:19], v155
	s_waitcnt lgkmcnt(0)
	ds_write_b64 v25, v[22:23]
	s_waitcnt vmcnt(15)
	ds_write_b128 v159, v[26:29]
	s_waitcnt vmcnt(14)
	ds_write_b128 v160, v[30:33] offset:256
	s_waitcnt vmcnt(13)
	ds_write_b128 v161, v[34:37] offset:512
	s_waitcnt vmcnt(12)
	ds_write_b128 v162, v[38:41] offset:768
	s_waitcnt vmcnt(11)
	ds_write_b128 v159, v[42:45] offset:4096
	s_waitcnt vmcnt(10)
	ds_write_b128 v160, v[46:49] offset:4352
	s_waitcnt vmcnt(9)
	ds_write_b128 v161, v[70:73] offset:4608
	s_waitcnt vmcnt(8)
	ds_write_b128 v162, v[116:119] offset:4864
	ds_read2_b64 v[26:29], v24 offset0:48 offset1:52
	ds_read_b128 v[36:39], v163 offset:256
	s_waitcnt lgkmcnt(11)
	v_mfma_f32_16x16x32_bf16 v[50:53], v[8:11], v[180:183], v[50:53]
	v_cmp_eq_u32_e64 s[8:9], 1, v132
	s_waitcnt lgkmcnt(1)
	v_lshlrev_b32_e32 v22, 8, v26
	v_and_b32_e32 v124, 0xffff00, v22
	v_lshlrev_b32_e32 v25, 8, v27
	v_lshl_add_u64 v[22:23], v[20:21], 0, v[124:125]
	v_lshlrev_b32_sdwa v124, v133, v26 dst_sel:DWORD dst_unused:UNUSED_PAD src0_sel:DWORD src1_sel:WORD_1
	v_lshl_add_u64 v[34:35], v[20:21], 0, v[124:125]
	v_and_b32_e32 v124, 0xffff00, v25
	v_lshlrev_b32_e32 v44, 8, v28
	global_load_dwordx4 v[30:33], v[22:23], off
	global_load_dwordx4 v[40:43], v[34:35], off
	v_lshl_add_u64 v[22:23], v[20:21], 0, v[124:125]
	v_lshlrev_b32_sdwa v124, v133, v27 dst_sel:DWORD dst_unused:UNUSED_PAD src0_sel:DWORD src1_sel:WORD_1
	v_lshl_add_u64 v[26:27], v[20:21], 0, v[124:125]
	v_and_b32_e32 v124, 0xffff00, v44
	v_lshlrev_b32_e32 v48, 8, v29
	global_load_dwordx4 v[44:47], v[22:23], off
	global_load_dwordx4 v[180:183], v[26:27], off
	v_lshl_add_u64 v[22:23], v[20:21], 0, v[124:125]
	v_lshlrev_b32_sdwa v124, v133, v28 dst_sel:DWORD dst_unused:UNUSED_PAD src0_sel:DWORD src1_sel:WORD_1
	v_lshl_add_u64 v[26:27], v[20:21], 0, v[124:125]
	v_and_b32_e32 v124, 0xffff00, v48
	v_mfma_f32_16x16x32_bf16 v[102:105], v[8:11], v[188:191], v[102:105]
	v_mfma_f32_16x16x32_bf16 v[98:101], v[8:11], v[184:187], v[98:101]
	global_load_dwordx4 v[184:187], v[22:23], off
	global_load_dwordx4 v[188:191], v[26:27], off
	v_lshl_add_u64 v[22:23], v[20:21], 0, v[124:125]
	v_lshlrev_b32_sdwa v124, v133, v29 dst_sel:DWORD dst_unused:UNUSED_PAD src0_sel:DWORD src1_sel:WORD_1
	v_mfma_f32_16x16x32_bf16 v[106:109], v[8:11], v[192:195], v[108:111]
	v_lshl_add_u64 v[34:35], v[20:21], 0, v[124:125]
	global_load_dwordx4 v[26:29], v[22:23], off
	global_load_dwordx4 v[192:195], v[34:35], off
	v_mfma_f32_16x16x32_bf16 v[112:115], v[8:11], v[196:199], v[112:115]
	v_mfma_f32_16x16x32_bf16 v[176:179], v[8:11], v[176:179], v[58:61]
	v_mfma_f32_16x16x32_bf16 v[120:123], v[8:11], v[120:123], v[54:57]
	ds_read_b64_tr_b16 v[212:213], v140
	ds_read_b64_tr_b16 v[214:215], v141
	ds_read_b64_tr_b16 v[208:209], v142
	ds_read_b64_tr_b16 v[210:211], v143
	ds_read_b64_tr_b16 v[204:205], v144
	ds_read_b64_tr_b16 v[206:207], v145
	ds_read_b64_tr_b16 v[200:201], v146
	ds_read_b64_tr_b16 v[202:203], v147
	ds_read_b64_tr_b16 v[196:197], v148
	ds_read_b64_tr_b16 v[198:199], v149
	ds_read_b64_tr_b16 v[116:117], v150
	ds_read_b64_tr_b16 v[118:119], v151
	ds_read_b64_tr_b16 v[70:71], v152
	ds_read_b64_tr_b16 v[72:73], v153
	ds_read_b64_tr_b16 v[56:57], v154
	ds_read_b64_tr_b16 v[58:59], v155
	s_waitcnt lgkmcnt(0)
; #define CBAR() asm volatile("" ::: "memory")
; __device__ __forceinline__ void dsa_pv_stream(KParams& p, unsigned char* smem) {
;     ...
;         for (int s = 0; s < 8; ++s) {
;             if (s == 4) { *(u32x2*)(ln + lane * 4) = idxN; CBAR(); }
; #pragma unroll
;             for (int j = 0; j < 4; ++j) { *(u32x4*)(vim + wof[0][j]) = vx[(2 * s) & 3][j]; *(u32x4*)(vim + wof[1][j]) = vx[(2 * s + 1) & 3][j]; }
;             CBAR();
;             if (2 * s + 4 < 16) { PV_ISSUE((2 * s) & 3, lc, 2 * s + 4, vbc); PV_ISSUE((2 * s + 1) & 3, lc, 2 * s + 5, vbc); }
;             else { PV_ISSUE((2 * s) & 3, ln, 2 * s + 4 - 16, vbn); PV_ISSUE((2 * s + 1) & 3, ln, 2 * s + 5 - 16, vbn); }
;             const u32x4 xf = *(const u32x4*)(pim + xoff + s * 64);
;             u32x2 y[16];
;             asm volatile("ds_read_b64_tr_b16 %0, %16\n\tds_read_b64_tr_b16 %1, %17\n\tds_read_b64_tr_b16 %2, %18\n\tds_read_b64_tr_b16 %3, %19\n\t"
;                          "ds_read_b64_tr_b16 %4, %20\n\tds_read_b64_tr_b16 %5, %21\n\tds_read_b64_tr_b16 %6, %22\n\tds_read_b64_tr_b16 %7, %23\n\t"
;                          "ds_read_b64_tr_b16 %8, %24\n\tds_read_b64_tr_b16 %9, %25\n\tds_read_b64_tr_b16 %10, %26\n\tds_read_b64_tr_b16 %11, %27\n\t"
;                          "ds_read_b64_tr_b16 %12, %28\n\tds_read_b64_tr_b16 %13, %29\n\tds_read_b64_tr_b16 %14, %30\n\tds_read_b64_tr_b16 %15, %31\n\t"
;                          "s_waitcnt lgkmcnt(0)"
;                          : "=&v"(y[0]), "=&v"(y[1]), "=&v"(y[2]), "=&v"(y[3]), "=&v"(y[4]), "=&v"(y[5]), "=&v"(y[6]), "=&v"(y[7]),
;                            "=&v"(y[8]), "=&v"(y[9]), "=&v"(y[10]), "=&v"(y[11]), "=&v"(y[12]), "=&v"(y[13]), "=&v"(y[14]), "=&v"(y[15])
;                          : "v"(tra[0]), "v"(tra[1]), "v"(tra[2]), "v"(tra[3]), "v"(tra[4]), "v"(tra[5]), "v"(tra[6]), "v"(tra[7]),
;                            "v"(tra[8]), "v"(tra[9]), "v"(tra[10]), "v"(tra[11]), "v"(tra[12]), "v"(tra[13]), "v"(tra[14]), "v"(tra[15])
;                          : "memory");
; #pragma unroll
;             for (int n = 0; n < 8; ++n) { const u32x4 yf = {y[2 * n].x, y[2 * n].y, y[2 * n + 1].x, y[2 * n + 1].y}; acc[n] = mfma16(xf, yf, acc[n]); }
	s_waitcnt vmcnt(15)
	ds_write_b128 v159, v[66:69]
	s_waitcnt vmcnt(11)
	ds_write_b128 v159, v[86:89] offset:4096
	ds_write_b128 v160, v[74:77] offset:256
	s_waitcnt vmcnt(10)
	ds_write_b128 v160, v[90:93] offset:4352
	ds_write_b128 v161, v[78:81] offset:512
	s_waitcnt vmcnt(9)
	ds_write_b128 v161, v[62:65] offset:4608
	ds_write_b128 v162, v[82:85] offset:768
	s_waitcnt vmcnt(8)
	ds_write_b128 v162, v[94:97] offset:4864
	ds_read2_b64 v[22:25], v24 offset0:56 offset1:60
	ds_read_b128 v[92:95], v163 offset:320
	s_waitcnt lgkmcnt(10)
	v_mfma_f32_16x16x32_bf16 v[48:51], v[36:39], v[196:199], v[50:53]
	s_waitcnt lgkmcnt(1)
	v_lshlrev_b32_e32 v34, 8, v22
	v_and_b32_e32 v124, 0xffff00, v34
	v_lshlrev_b32_e32 v62, 8, v23
	v_lshl_add_u64 v[34:35], v[20:21], 0, v[124:125]
	v_lshlrev_b32_sdwa v124, v133, v22 dst_sel:DWORD dst_unused:UNUSED_PAD src0_sel:DWORD src1_sel:WORD_1
	v_lshl_add_u64 v[60:61], v[20:21], 0, v[124:125]
	v_and_b32_e32 v124, 0xffff00, v62
	v_mfma_f32_16x16x32_bf16 v[52:55], v[36:39], v[116:119], v[176:179]
	v_lshlrev_b32_e32 v64, 8, v24
	v_lshlrev_b32_e32 v76, 8, v25
	v_mfma_f32_16x16x32_bf16 v[176:179], v[36:39], v[70:73], v[120:123]
	global_load_dwordx4 v[68:71], v[34:35], off
	s_nop 0
	global_load_dwordx4 v[60:63], v[60:61], off
	v_lshl_add_u64 v[34:35], v[20:21], 0, v[124:125]
	v_lshlrev_b32_sdwa v124, v133, v23 dst_sel:DWORD dst_unused:UNUSED_PAD src0_sel:DWORD src1_sel:WORD_1
	v_lshl_add_u64 v[22:23], v[20:21], 0, v[124:125]
	v_and_b32_e32 v124, 0xffff00, v64
	global_load_dwordx4 v[72:75], v[34:35], off
	global_load_dwordx4 v[64:67], v[22:23], off
	v_lshl_add_u64 v[22:23], v[20:21], 0, v[124:125]
	v_lshlrev_b32_sdwa v124, v133, v24 dst_sel:DWORD dst_unused:UNUSED_PAD src0_sel:DWORD src1_sel:WORD_1
	v_lshl_add_u64 v[34:35], v[20:21], 0, v[124:125]
	v_and_b32_e32 v124, 0xffff00, v76
	global_load_dwordx4 v[84:87], v[22:23], off
	global_load_dwordx4 v[76:79], v[34:35], off
	v_lshl_add_u64 v[22:23], v[20:21], 0, v[124:125]
	v_lshlrev_b32_sdwa v124, v133, v25 dst_sel:DWORD dst_unused:UNUSED_PAD src0_sel:DWORD src1_sel:WORD_1
	v_lshl_add_u64 v[20:21], v[20:21], 0, v[124:125]
	global_load_dwordx4 v[88:91], v[22:23], off
	global_load_dwordx4 v[80:83], v[20:21], off
	v_mfma_f32_16x16x32_bf16 v[110:113], v[36:39], v[212:215], v[112:115]
	v_mfma_f32_16x16x32_bf16 v[106:109], v[36:39], v[208:211], v[106:109]
	v_mfma_f32_16x16x32_bf16 v[102:105], v[36:39], v[204:207], v[102:105]
	v_mfma_f32_16x16x32_bf16 v[200:203], v[36:39], v[200:203], v[98:101]
	ds_read_b64_tr_b16 v[212:213], v140
	ds_read_b64_tr_b16 v[214:215], v141
	ds_read_b64_tr_b16 v[208:209], v142
	ds_read_b64_tr_b16 v[210:211], v143
	ds_read_b64_tr_b16 v[204:205], v144
	ds_read_b64_tr_b16 v[206:207], v145
	ds_read_b64_tr_b16 v[196:197], v146
	ds_read_b64_tr_b16 v[198:199], v147
	ds_read_b64_tr_b16 v[116:117], v148
	ds_read_b64_tr_b16 v[118:119], v149
	ds_read_b64_tr_b16 v[120:121], v150
	ds_read_b64_tr_b16 v[122:123], v151
	ds_read_b64_tr_b16 v[20:21], v152
	ds_read_b64_tr_b16 v[22:23], v153
	ds_read_b64_tr_b16 v[96:97], v154
	ds_read_b64_tr_b16 v[98:99], v155
	s_waitcnt lgkmcnt(0)
	s_waitcnt vmcnt(15)
	ds_write_b128 v159, v[30:33]
	s_waitcnt vmcnt(14)
	ds_write_b128 v160, v[40:43] offset:256
	s_waitcnt vmcnt(13)
	ds_write_b128 v161, v[44:47] offset:512
	s_waitcnt vmcnt(12)
	ds_write_b128 v162, v[180:183] offset:768
	s_waitcnt vmcnt(11)
	ds_write_b128 v159, v[184:187] offset:4096
	s_waitcnt vmcnt(10)
	ds_write_b128 v160, v[188:191] offset:4352
	s_waitcnt vmcnt(9)
	ds_write_b128 v161, v[26:29] offset:4608
	s_waitcnt vmcnt(8)
	ds_write_b128 v162, v[192:195] offset:4864
	s_waitcnt lgkmcnt(8)
	v_mfma_f32_16x16x32_bf16 v[212:215], v[92:95], v[212:215], v[110:113]
	v_mfma_f32_16x16x32_bf16 v[208:211], v[92:95], v[208:211], v[106:109]
	v_mfma_f32_16x16x32_bf16 v[108:111], v[92:95], v[204:207], v[102:105]
	v_mfma_f32_16x16x32_bf16 v[116:119], v[92:95], v[116:119], v[48:51]
	s_nop 2
	ds_read2_b64 v[46:49], v135 offset1:4
	ds_read_b128 v[100:103], v163 offset:384
	s_waitcnt lgkmcnt(1)
	v_lshlrev_b32_e32 v30, 8, v48
	v_mfma_f32_16x16x32_bf16 v[176:179], v[92:95], v[20:23], v[176:179]
	v_lshlrev_b32_e32 v20, 8, v46
	v_and_b32_e32 v124, 0xffff00, v20
	v_lshlrev_b32_e32 v22, 8, v47
	v_lshl_add_u64 v[20:21], v[136:137], 0, v[124:125]
	v_lshlrev_b32_sdwa v124, v133, v46 dst_sel:DWORD dst_unused:UNUSED_PAD src0_sel:DWORD src1_sel:WORD_1
	v_lshl_add_u64 v[24:25], v[136:137], 0, v[124:125]
	v_and_b32_e32 v124, 0xffff00, v22
	v_lshl_add_u64 v[28:29], v[136:137], 0, v[124:125]
	v_lshlrev_b32_sdwa v124, v133, v47 dst_sel:DWORD dst_unused:UNUSED_PAD src0_sel:DWORD src1_sel:WORD_1
	v_lshl_add_u64 v[32:33], v[136:137], 0, v[124:125]
	v_and_b32_e32 v124, 0xffff00, v30
	v_lshlrev_b32_e32 v42, 8, v49
	v_lshl_add_u64 v[40:41], v[136:137], 0, v[124:125]
	v_lshlrev_b32_sdwa v124, v133, v48 dst_sel:DWORD dst_unused:UNUSED_PAD src0_sel:DWORD src1_sel:WORD_1
	v_lshl_add_u64 v[44:45], v[136:137], 0, v[124:125]
	v_and_b32_e32 v124, 0xffff00, v42
	v_mfma_f32_16x16x32_bf16 v[120:123], v[92:95], v[120:123], v[52:55]
	v_lshl_add_u64 v[50:51], v[136:137], 0, v[124:125]
	v_lshlrev_b32_sdwa v124, v133, v49 dst_sel:DWORD dst_unused:UNUSED_PAD src0_sel:DWORD src1_sel:WORD_1
	v_lshl_add_u64 v[48:49], v[136:137], 0, v[124:125]
	v_mfma_f32_16x16x32_bf16 v[112:115], v[92:95], v[196:199], v[200:203]
	global_load_dwordx4 v[20:23], v[20:21], off
	s_nop 0
	global_load_dwordx4 v[24:27], v[24:25], off
	s_nop 0
	global_load_dwordx4 v[28:31], v[28:29], off
	s_nop 0
	global_load_dwordx4 v[32:35], v[32:33], off
	s_nop 0
	global_load_dwordx4 v[40:43], v[40:41], off
	s_nop 0
	global_load_dwordx4 v[44:47], v[44:45], off
	s_nop 0
	global_load_dwordx4 v[52:55], v[50:51], off
	s_nop 0
	global_load_dwordx4 v[48:51], v[48:49], off
	ds_read_b64_tr_b16 v[204:205], v140
	ds_read_b64_tr_b16 v[206:207], v141
	ds_read_b64_tr_b16 v[200:201], v142
	ds_read_b64_tr_b16 v[202:203], v143
	ds_read_b64_tr_b16 v[196:197], v144
	ds_read_b64_tr_b16 v[198:199], v145
	ds_read_b64_tr_b16 v[192:193], v146
	ds_read_b64_tr_b16 v[194:195], v147
	ds_read_b64_tr_b16 v[188:189], v148
	ds_read_b64_tr_b16 v[190:191], v149
	ds_read_b64_tr_b16 v[184:185], v150
	ds_read_b64_tr_b16 v[186:187], v151
	ds_read_b64_tr_b16 v[180:181], v152
	ds_read_b64_tr_b16 v[182:183], v153
	ds_read_b64_tr_b16 v[104:105], v154
	ds_read_b64_tr_b16 v[106:107], v155
	s_waitcnt lgkmcnt(0)
; __device__ __forceinline__ unsigned short f2bf(float f) { return (unsigned short)(cvt_pk_bf16(f, 0.f) & 0xffffu); }
; #define CBAR() asm volatile("" ::: "memory")
; __device__ __forceinline__ void dsa_pv_stream(KParams& p, unsigned char* smem) {
;     ...
;             for (int n = 0; n < 8; ++n) { const u32x4 yf = {y[2 * n].x, y[2 * n].y, y[2 * n + 1].x, y[2 * n + 1].y}; acc[n] = mfma16(xf, yf, acc[n]); }
;         }
;         CBAR();
;         {
;             const int hc = ((bg & 1) * 4 + fq) * 128;
; #pragma unroll
;             for (int n = 0; n < 8; ++n) {
;                 const float o = fq == 0 ? acc[n][0] : fq == 1 ? acc[n][1] : fq == 2 ? acc[n][2] : acc[n][3];
;                 ((unsigned short*)pim)[fq * 128 + n * 16 + fr] = f2bf(o * p.dsa_beta[hc + n * 16 + fr]);
;             }
;             CBAR();
;             const u32x4 ov = *(const u32x4*)(pim + lane * 16);
;             *(u32x4*)((bf16_t*)(p.ws + WS_Y) + tok * DM + 1024 + (bg & 1) * 512 + lane * 8) = ov;
;             CBAR();
;             *(u32x4*)(pim + lane * 32) = pN0; *(u32x4*)(pim + lane * 32 + 16) = pN1;
;             CBAR();
	s_waitcnt vmcnt(15)
	ds_write_b128 v159, v[68:71]
	s_waitcnt vmcnt(11)
	ds_write_b128 v159, v[84:87] offset:4096
	ds_write_b128 v160, v[60:63] offset:256
	s_waitcnt vmcnt(10)
	ds_write_b128 v160, v[76:79] offset:4352
	ds_write_b128 v161, v[72:75] offset:512
	s_waitcnt vmcnt(9)
	ds_write_b128 v161, v[88:91] offset:4608
	ds_write_b128 v162, v[64:67] offset:768
	s_waitcnt vmcnt(8)
	ds_write_b128 v162, v[80:83] offset:4864
	s_waitcnt lgkmcnt(8)
	v_mfma_f32_16x16x32_bf16 v[120:123], v[100:103], v[184:187], v[120:123]
	ds_read2_b64 v[82:85], v135 offset0:8 offset1:12
	ds_read_b128 v[184:187], v163 offset:448
	v_or_b32_e32 v124, s39, v157
	v_lshlrev_b32_e32 v175, 2, v124
	v_mfma_f32_16x16x32_bf16 v[204:207], v[100:103], v[204:207], v[212:215]
	s_waitcnt lgkmcnt(1)
	v_lshlrev_b32_e32 v60, 8, v82
	v_and_b32_e32 v124, 0xffff00, v60
	v_lshlrev_b32_e32 v64, 8, v83
	v_lshl_add_u64 v[60:61], v[136:137], 0, v[124:125]
	v_lshlrev_b32_sdwa v124, v133, v82 dst_sel:DWORD dst_unused:UNUSED_PAD src0_sel:DWORD src1_sel:WORD_1
	v_lshl_add_u64 v[62:63], v[136:137], 0, v[124:125]
	v_and_b32_e32 v124, 0xffff00, v64
	v_lshlrev_b32_e32 v72, 8, v84
	v_lshl_add_u64 v[68:69], v[136:137], 0, v[124:125]
	v_lshlrev_b32_sdwa v124, v133, v83 dst_sel:DWORD dst_unused:UNUSED_PAD src0_sel:DWORD src1_sel:WORD_1
	v_lshl_add_u64 v[70:71], v[136:137], 0, v[124:125]
	v_and_b32_e32 v124, 0xffff00, v72
	v_lshlrev_b32_e32 v80, 8, v85
	v_lshl_add_u64 v[76:77], v[136:137], 0, v[124:125]
	v_lshlrev_b32_sdwa v124, v133, v84 dst_sel:DWORD dst_unused:UNUSED_PAD src0_sel:DWORD src1_sel:WORD_1
	v_lshl_add_u64 v[78:79], v[136:137], 0, v[124:125]
	v_and_b32_e32 v124, 0xffff00, v80
	v_lshl_add_u64 v[86:87], v[136:137], 0, v[124:125]
	v_lshlrev_b32_sdwa v124, v133, v85 dst_sel:DWORD dst_unused:UNUSED_PAD src0_sel:DWORD src1_sel:WORD_1
	v_lshl_add_u64 v[84:85], v[136:137], 0, v[124:125]
	v_mfma_f32_16x16x32_bf16 v[200:203], v[100:103], v[200:203], v[208:211]
	global_load_dwordx4 v[64:67], v[60:61], off
	s_nop 0
	global_load_dwordx4 v[60:63], v[62:63], off
	s_nop 0
	global_load_dwordx4 v[72:75], v[68:69], off
	s_nop 0
	global_load_dwordx4 v[68:71], v[70:71], off
	s_nop 0
	global_load_dwordx4 v[80:83], v[76:77], off
	s_nop 0
	global_load_dwordx4 v[76:79], v[78:79], off
	v_mfma_f32_16x16x32_bf16 v[108:111], v[100:103], v[196:199], v[108:111]
	global_load_dwordx4 v[88:91], v[86:87], off
	s_nop 0
	global_load_dwordx4 v[84:87], v[84:85], off
	v_mfma_f32_16x16x32_bf16 v[112:115], v[100:103], v[192:195], v[112:115]
	v_mfma_f32_16x16x32_bf16 v[116:119], v[100:103], v[188:191], v[116:119]
	v_mfma_f32_16x16x32_bf16 v[176:179], v[100:103], v[180:183], v[176:179]
	ds_read_b64_tr_b16 v[220:221], v140
	ds_read_b64_tr_b16 v[222:223], v141
	ds_read_b64_tr_b16 v[216:217], v142
	ds_read_b64_tr_b16 v[218:219], v143
	ds_read_b64_tr_b16 v[212:213], v144
	ds_read_b64_tr_b16 v[214:215], v145
	ds_read_b64_tr_b16 v[208:209], v146
	ds_read_b64_tr_b16 v[210:211], v147
	ds_read_b64_tr_b16 v[196:197], v148
	ds_read_b64_tr_b16 v[198:199], v149
	ds_read_b64_tr_b16 v[192:193], v150
	ds_read_b64_tr_b16 v[194:195], v151
	ds_read_b64_tr_b16 v[188:189], v152
	ds_read_b64_tr_b16 v[190:191], v153
	ds_read_b64_tr_b16 v[180:181], v154
	ds_read_b64_tr_b16 v[182:183], v155
	s_waitcnt lgkmcnt(0)
	s_waitcnt lgkmcnt(0)
	v_mfma_f32_16x16x32_bf16 v[204:207], v[184:187], v[220:223], v[204:207]
	v_mfma_f32_16x16x32_bf16 v[200:203], v[184:187], v[216:219], v[200:203]
	v_mfma_f32_16x16x32_bf16 v[108:111], v[184:187], v[212:215], v[108:111]
	s_nop 5
	v_cndmask_b32_e64 v135, v204, v205, s[8:9]
	v_cndmask_b32_e64 v135, v135, v206, s[10:11]
	v_cndmask_b32_e64 v135, v135, v207, s[12:13]
	v_cndmask_b32_e64 v136, v200, v201, s[8:9]
	v_cndmask_b32_e64 v136, v136, v202, s[10:11]
	v_cndmask_b32_e64 v136, v136, v203, s[12:13]
	v_cndmask_b32_e64 v108, v108, v109, s[8:9]
	v_cndmask_b32_e64 v108, v108, v110, s[10:11]
	v_cndmask_b32_e64 v108, v108, v111, s[12:13]
	v_mfma_f32_16x16x32_bf16 v[8:11], v[8:11], v[16:19], v[12:15]
	v_mul_f32_e32 v124, v135, v224
	v_cvt_pk_bf16_f32 v124, v124, v125
	ds_write_b16 v158, v124
	v_mfma_f32_16x16x32_bf16 v[8:11], v[36:39], v[56:59], v[8:11]
	v_mul_f32_e32 v124, v136, v225
	v_cvt_pk_bf16_f32 v124, v124, v125
	ds_write_b16 v158, v124 offset:32
	v_mfma_f32_16x16x32_bf16 v[8:11], v[92:95], v[96:99], v[8:11]
	v_mul_f32_e32 v108, v108, v226
	v_cvt_pk_bf16_f32 v124, v108, v125
	v_mfma_f32_16x16x32_bf16 v[108:111], v[184:187], v[208:211], v[112:115]
	ds_write_b16 v158, v124 offset:64
	v_mfma_f32_16x16x32_bf16 v[8:11], v[100:103], v[104:107], v[8:11]
	v_mfma_f32_16x16x32_bf16 v[8:11], v[184:187], v[180:183], v[8:11]
	s_nop 4
	v_cndmask_b32_e64 v108, v108, v109, s[8:9]
	v_cndmask_b32_e64 v108, v108, v110, s[10:11]
	v_cndmask_b32_e64 v108, v108, v111, s[12:13]
	v_mul_f32_e32 v108, v108, v227
	v_cvt_pk_bf16_f32 v112, v108, v125
	v_mfma_f32_16x16x32_bf16 v[108:111], v[184:187], v[196:199], v[116:119]
	ds_write_b16 v158, v112 offset:96
	v_cndmask_b32_e64 v8, v8, v9, s[8:9]
	v_cndmask_b32_e64 v8, v8, v10, s[10:11]
	v_cndmask_b32_e64 v8, v8, v11, s[12:13]
	v_mov_b32_e32 v135, v125
	s_nop 2
	v_cndmask_b32_e64 v108, v108, v109, s[8:9]
	v_cndmask_b32_e64 v108, v108, v110, s[10:11]
	v_cndmask_b32_e64 v108, v108, v111, s[12:13]
	v_lshl_add_u64 v[12:13], s[4:5], 0, v[134:135]
	v_add_co_u32_e32 v12, vcc, 0x29730000, v12
	v_mul_f32_e32 v108, v108, v228
	v_cvt_pk_bf16_f32 v112, v108, v125
	v_mfma_f32_16x16x32_bf16 v[108:111], v[184:187], v[192:195], v[120:123]
	ds_write_b16 v158, v112 offset:128
	v_addc_co_u32_e32 v13, vcc, 0, v13, vcc
	s_nop 5
	v_cndmask_b32_e64 v108, v108, v109, s[8:9]
	v_cndmask_b32_e64 v108, v108, v110, s[10:11]
	v_cndmask_b32_e64 v108, v108, v111, s[12:13]
	v_mul_f32_e32 v108, v108, v229
	v_cvt_pk_bf16_f32 v112, v108, v125
	v_mfma_f32_16x16x32_bf16 v[108:111], v[184:187], v[188:191], v[176:179]
	ds_write_b16 v158, v112 offset:160
	s_nop 6
	v_cndmask_b32_e64 v108, v108, v109, s[8:9]
	v_cndmask_b32_e64 v108, v108, v110, s[10:11]
	v_cndmask_b32_e64 v108, v108, v111, s[12:13]
	s_mov_b32 s9, s16
	v_mul_f32_e32 v108, v108, v230
	v_cvt_pk_bf16_f32 v108, v108, v125
	ds_write_b16 v158, v108 offset:192
	v_mul_f32_e32 v8, v8, v231
	v_cvt_pk_bf16_f32 v8, v8, v125
	ds_write_b16 v158, v8 offset:224
	ds_read_b128 v[8:11], v164
	s_waitcnt lgkmcnt(0)
	global_store_dwordx4 v[12:13], v[8:11], off offset:2048
	ds_write_b128 v165, v[4:7]
	ds_write_b128 v165, v[0:3] offset:16
	s_cbranch_scc1 .LBB0_1771
	s_branch .LBB0_1768
